# P11 idle CUs (3 of 3.5 GEMM rounds) convert half of the layer-1 MLP weights (w_mlp_in) before seam 11; P12 converts only w_mlp_out
# speedup vs baseline: 1.0754x; 1.0005x over previous
; #define LAS __attribute__((address_space(3)))
; __device__ __forceinline__ unsigned xb_add(unsigned* p, unsigned v) { return __hip_atomic_fetch_add(p, v, __ATOMIC_RELAXED, __HIP_MEMORY_SCOPE_AGENT); }
; __device__ __forceinline__ unsigned xb_xcc_id() { return (unsigned)__builtin_amdgcn_s_getreg((3 << 11) | 20) & 0xFu; }
; __global__ void __launch_bounds__(512, 2) fwd_kernel(Params p) {
;     extern __shared__ __attribute__((aligned(16))) unsigned char lds_raw[];
;     LAS unsigned char* lds = (LAS unsigned char*)lds_raw;
;     LAS int* s_item = (LAS int*)(lds + LDS_MISC);
;     if (threadIdx.x < 64) ((LAS unsigned*)(lds + LDS_MISC))[threadIdx.x] = 0u;
;     __syncthreads();
;     cg::grid_group grid = cg::this_grid();
;     const int lo = p.ph_lo, hi = p.ph_hi;
;     if (hi > NPHASE + 7) grid.sync();
;     if (hi - lo > 1 && threadIdx.x == 0) (void)xb_add((unsigned*)(p.ws + WS_CTL) + 4096 + XB_XCNT(xb_xcc_id()), 1u);
_Z10fwd_kernel6Params:
	s_load_dwordx2 s[80:81], s[0:1], 0xe8
	s_mov_b32 s101, 0
	v_and_b32_e32 v193, 0x3ff, v0
	s_mov_b32 s84, s2
	s_mov_b64 s[78:79], s[0:1]
	v_cmp_gt_u32_e32 vcc, 64, v193
	s_and_saveexec_b64 s[4:5], vcc
	v_lshl_add_u32 v1, v193, 2, 0
	v_add_u32_e32 v1, 0x21000, v1
	v_mov_b32_e32 v2, 0
	ds_write_b32 v1, v2
	s_or_b64 exec, exec, s[4:5]
	s_waitcnt lgkmcnt(0)
	s_barrier
	s_load_dwordx2 s[76:77], s[78:79], 0xf0
	s_load_dword s75, s[78:79], 0xf8
	s_add_u32 s6, s78, 0xf0
	s_addc_u32 s7, s79, 0
	s_cmp_lt_i32 s81, 28
	s_cbranch_scc1 .LBB0_14
	v_lshrrev_b32_e32 v1, 20, v0
	v_lshrrev_b32_e32 v0, 10, v0
	v_or_b32_e32 v0, v0, v1
	s_movk_i32 s0, 0x3ff
	v_and_or_b32 v0, v0, s0, v193
	v_cmp_eq_u32_e32 vcc, 0, v0
	s_waitcnt lgkmcnt(0)
	s_barrier
	s_and_saveexec_b64 s[4:5], vcc
	s_cbranch_execz .LBB0_13
	buffer_wbl2 sc1
	s_load_dwordx2 s[6:7], s[6:7], 0x58
	s_mov_b64 s[8:9], exec
	v_mbcnt_lo_u32_b32 v0, s8, 0
	v_mbcnt_hi_u32_b32 v0, s9, v0
	v_cmp_eq_u32_e32 vcc, 0, v0
	s_waitcnt lgkmcnt(0)
	s_load_dword s0, s[6:7], 0x28
	s_and_saveexec_b64 s[10:11], vcc
	s_cbranch_execz .LBB0_6
	s_bcnt1_i32_b64 s1, s[8:9]
	v_mov_b32_e32 v1, 0
	v_mov_b32_e32 v2, s1
	global_atomic_add v1, v1, v2, s[6:7] offset:32 sc0

; __device__ __forceinline__ unsigned xb_ld(unsigned* p)              { return __hip_atomic_load(p, __ATOMIC_RELAXED, __HIP_MEMORY_SCOPE_AGENT); }
; #define SEAM(k) do { if (lo <= (k) && (k) + 1 < hi) { CParams* P_ = (CParams*)__builtin_amdgcn_kernarg_segment_ptr(); asm volatile("" : "+s"(P_)); \
;         XcdBarrier b_; b_.bar = (unsigned*)(P_->ws + WS_CTL) + 4096; b_.x = xb_xcc_id(); b_.st = (volatile LAS unsigned*)(lds + LDS_MISC + 32); xcd_barrier(b_); } } while (0)
; __device__ __forceinline__ void xcd_barrier_complete(unsigned* bar, unsigned x, unsigned& nloc, unsigned& nx) {
;     const unsigned G = gridDim.x * gridDim.y * gridDim.z;
;     unsigned sum, cnt, mine, sp = 0u;
;     for (;;) {
;         sum = 0u; cnt = 0u; mine = 0u;
; #pragma unroll
;         for (unsigned j = 0; j < 16; ++j) { const unsigned c = xb_ld(&bar[XB_XCNT(j)]); sum += c; cnt += (c > 0u) ? 1u : 0u; mine = (j == x) ? c : mine; }
;         if (sum == G) break;
;         __builtin_amdgcn_s_sleep(1);
;         if ((++sp & 255u) == 0u) { if (xb_ld(&bar[XB_TMO])) break; if (sp > XB_SPIN_CAP) { atomicAdd(&bar[XB_TMO], 1u); break; } }
;     }
;     nloc = mine > 0u ? mine : 1u; nx = cnt > 0u ? cnt : 1u;
; }
; __device__ __forceinline__ void xcd_barrier(const XcdBarrier& b) {
;     asm volatile("s_waitcnt vmcnt(0)" ::: "memory");
;     __syncthreads();
;     if (threadIdx.x == 0) {
;         unsigned* bar = b.bar;
;         __builtin_amdgcn_s_waitcnt(0);
;         unsigned nloc = b.st[0], nx = b.st[1];
;         if (nloc == 0u) { xcd_barrier_complete(bar, b.x, nloc, nx); b.st[0] = nloc; b.st[1] = nx; }
; __global__ void __launch_bounds__(512, 2) fwd_kernel(Params p) {
;     ...
;     SEAM(11);
.LBB0_1142:
	s_cmp_gt_i32 s81, 12
	s_cselect_b64 s[4:5], -1, 0
	s_and_b64 s[0:1], s[8:9], s[4:5]
	s_andn2_b64 vcc, exec, s[0:1]
	s_cbranch_vccnz .LBB0_1196
	s_cmp_lt_u32 s84, 0x80
	s_cbranch_scc1 .Lp11_no_excursion
	s_mov_b32 s101, 1
	s_movk_i32 s98, 0xfff
	s_mov_b32 s99, s76
	s_sub_i32 s84, s84, 0x80
	s_movk_i32 s76, 0x80
	s_branch .Lp12_conv_entry
.Lp11_excursion_return:
	s_mov_b32 s101, 0
	s_mov_b32 s76, s99
	s_add_i32 s84, s84, 0x80
	s_cmp_gt_i32 s81, 12
	s_cselect_b64 s[4:5], -1, 0
.Lp11_no_excursion:
	s_mov_b64 s[8:9], s[78:79]
	s_getreg_b32 s0, hwreg(HW_REG_XCC_ID, 0, 4)
	s_waitcnt vmcnt(0)
	s_waitcnt vmcnt(0) lgkmcnt(0)
	s_barrier
	s_and_saveexec_b64 s[6:7], s[82:83]
	s_cbranch_execz .LBB0_1195
	s_add_i32 s1, 0, 0x21020
	v_mov_b32_e32 v0, s1
	s_load_dwordx2 s[8:9], s[8:9], 0xe0
	s_waitcnt vmcnt(0) expcnt(0) lgkmcnt(0)
	ds_read_b32 v2, v0
	s_add_i32 s1, 0, 0x21024
	v_mov_b32_e32 v0, s1
	ds_read_b32 v0, v0
	s_and_b32 s0, s0, 15
	s_waitcnt lgkmcnt(1)
	v_cmp_ne_u32_e32 vcc, 0, v2
	s_cbranch_vccnz .LBB0_1159
	s_add_u32 s10, s8, 0x4200
	s_addc_u32 s11, s9, 0
	s_add_u32 s12, s8, 0x4400
	s_addc_u32 s13, s9, 0
	s_add_u32 s14, s8, 0x4500
	s_addc_u32 s15, s9, 0
	s_add_u32 s16, s8, 0x4600
	s_addc_u32 s17, s9, 0
	s_add_u32 s18, s8, 0x4700
	s_addc_u32 s19, s9, 0
	s_add_u32 s20, s8, 0x4800
	s_addc_u32 s21, s9, 0
	s_add_u32 s22, s8, 0x4900
	s_addc_u32 s23, s9, 0
	s_add_u32 s24, s8, 0x4a00
	s_addc_u32 s25, s9, 0
	s_add_u32 s26, s8, 0x4b00
	s_addc_u32 s27, s9, 0
	s_add_u32 s28, s8, 0x4c00
	s_addc_u32 s29, s9, 0
	s_add_u32 s30, s8, 0x4d00
	s_addc_u32 s31, s9, 0
	s_add_u32 s34, s8, 0x4e00
	s_addc_u32 s35, s9, 0
	s_add_u32 s36, s8, 0x4f00
	s_addc_u32 s37, s9, 0
	s_add_u32 s40, s8, 0x5000
	s_addc_u32 s41, s9, 0
	s_add_u32 s42, s8, 0x5100
	s_addc_u32 s43, s9, 0
	s_add_u32 s44, s8, 0x5200
	s_addc_u32 s45, s9, 0
	s_mul_i32 s1, s77, s75
	s_add_u32 s46, s8, 0x5300
	s_mul_i32 s1, s1, s76
	s_addc_u32 s47, s9, 0
	s_mov_b32 s2, 1
	v_mov_b32_e32 v16, 0
	s_branch .LBB0_1147

; #define LAS __attribute__((address_space(3)))
; #define PH(k) if (((PHMASK >> (k)) & 1) && lo <= (k) && (k) < hi) for (int rep_ = 0; rep_ < 1 + ((REPMASK >> (k)) & 1); ++rep_)
; #define P12_SELECT(it_, t) do { int r = (it_); if (tr_job(r, P->w_mlp_in + (size_t)2048 * 8192, 2048, 8192, Wmi1_t, P->mlp_norm + DM, t)) {} \
;               else tr_job(r, P->w_mlp_out + (size_t)2048 * 8192, 8192, 2048, Wmo1_t, nullptr, t); } while (0)
; __global__ void __launch_bounds__(512, 2) fwd_kernel(Params p) {
;     ...
;     PH(12) { PHASE_BEGIN;
;         { LAS float* scr = (LAS float*)(lds + wave * TR_SCR_BYTES); constexpr int NIT1 = 2 * (2048 / 64) * (8192 / 64);
;     ...
;           int it = gw; TrSel cur, nx; f32x4 v[16], nv[16]; float gg[16], ng[16];
;           if (it < NIT1) { P12_SELECT(it, cur); tr_load(cur, lane, v, gg); }
.Lp12_conv_entry:
	s_mov_b64 s[16:17], s[78:79]
	v_mov_b32_e32 v129, v193
	s_load_dwordx2 s[14:15], s[16:17], 0xe0
	v_readfirstlane_b32 s1, v129
	s_lshl_b32 s0, s84, 3
	s_ashr_i32 s1, s1, 6
	s_add_i32 s12, s1, s0
	s_cmp_eq_u32 s101, 1
	s_cbranch_scc1 .Lp12_keep_gw
	s_movk_i32 s98, 0x1fff
	s_addk_i32 s12, 0x1000
.Lp12_keep_gw:
	s_waitcnt lgkmcnt(0)
	s_add_u32 s2, s14, 0x8000000
	s_addc_u32 s3, s15, 0
	s_add_u32 s13, s14, 0xa000000
	s_addc_u32 s28, s15, 0
	s_cmp_le_i32 s12, s98
	s_cselect_b64 s[10:11], -1, 0
	v_and_b32_e32 v64, 63, v129
	s_cmp_gt_i32 s12, s98
	s_cbranch_scc1 .LBB0_1200
	s_cmpk_gt_i32 s12, 0xfff
	s_cselect_b64 s[4:5], -1, 0
	s_cmpk_lt_i32 s12, 0x1000
	s_cbranch_scc1 .LBB0_1201
	s_add_i32 s20, s12, 0xfffff000
	s_cbranch_execnz .LBB0_1203
	s_branch .LBB0_1202

; #define P12_SELECT(it_, t) do { int r = (it_); if (tr_job(r, P->w_mlp_in + (size_t)2048 * 8192, 2048, 8192, Wmi1_t, P->mlp_norm + DM, t)) {} \
;               else tr_job(r, P->w_mlp_out + (size_t)2048 * 8192, 8192, 2048, Wmo1_t, nullptr, t); } while (0)
; __device__ __forceinline__ bool tr_job(int& r, const float* W, int K, int N, bf16_t* WT, const float* gain, TrSel& t) {
;     const int nblk = N / 64, items = (K / 64) * nblk;
;     if (r >= items) { r -= items; return false; }
; __global__ void __launch_bounds__(512, 2) fwd_kernel(Params p) {
;     ...
;           while (it < NIT1) { const int nit = it + NGW;
;               if (nit < NIT1) { P12_SELECT(nit, nx); tr_load(nx, lane, nv, ng); }
.LBB0_1234:
	s_add_i32 s31, s31, s18
	s_cmp_gt_i32 s31, s98
	s_cselect_b64 s[24:25], -1, 0
	s_and_b64 vcc, exec, s[24:25]
	s_cbranch_vccnz .LBB0_1233
	s_cmpk_gt_i32 s31, 0xfff
	s_cselect_b64 s[4:5], -1, 0
	s_cmpk_lt_i32 s31, 0x1000
	s_mov_b64 s[26:27], -1
	s_cbranch_scc1 .LBB0_1255
	s_add_i32 s35, s31, 0xfffff000
	s_cbranch_execz .LBB0_1256

; __global__ void __launch_bounds__(512, 2) fwd_kernel(Params p) {
;     ...
;         for (int item = gw; item < (T / 32) * 3; item += NGW) { const int third = item % 3, m0 = (item / 3) * 32; const int c0 = third * 512 + lane * 8;
.LBB0_1257:
	s_cmp_eq_u32 s101, 1
	s_cbranch_scc1 .Lp11_excursion_return
	s_addk_i32 s12, 0xf000
	s_cmpk_gt_i32 s12, 0x5ff
	s_cbranch_scc1 .LBB0_1276
	s_load_dwordx4 s[8:11], s[16:17], 0xa0
	s_add_u32 s20, s14, 0x13000000
	s_addc_u32 s21, s15, 0
	s_add_u32 s2, s14, 0x17000000
	s_addc_u32 s3, s15, 0
	s_mov_b64 s[22:23], 0x1800
	s_movk_i32 s13, 0x1000
	s_mov_b64 s[24:25], 0x3000
	s_movk_i32 s19, 0x3000
	s_mov_b64 s[26:27], 0x4800
	s_movk_i32 s30, 0x4000
	v_mov_b32_e32 v154, 0xc00
	s_mov_b32 s31, s12
